# attention (3 V buffers, 1 barrier per tile): one static s_setprio 1 for waves 4-7 during the phase
# speedup vs baseline: 1.0108x; 1.0108x over previous
.LBB0_689:
	s_cmp_lt_i32 s30, 6
	s_cselect_b64 s[4:5], -1, 0
	s_cmp_gt_i32 s31, 5
	s_cselect_b64 s[6:7], -1, 0
	s_and_b64 s[4:5], s[4:5], s[6:7]
	s_andn2_b64 vcc, exec, s[4:5]
	s_cbranch_vccnz .LBB0_766
	s_mov_b64 s[6:7], s[0:1]
	v_mov_b32_e32 v1, v0
	s_cmpk_gt_i32 s48, 0x3ff
	s_cbranch_scc1 .LBB0_712
	v_readfirstlane_b32 s8, v0
	s_load_dwordx2 s[50:51], s[6:7], 0xe0
	s_lshr_b32 s8, s8, 6
	s_cmp_ge_u32 s8, 4
	s_cbranch_scc0 .Latt_prio_done
	s_setprio 1
